# cand2 + XCD-local barriers at the three GEMM-to-GEMM seams (w_out->ffn_in, ffn_in->ffn_out, ffn_out->proj): no L2 writeback / cross-XCD rendezvous there
# speedup vs baseline: 1.0117x; 1.0091x over previous
; __device__ __forceinline__ unsigned xb_add(unsigned* p, unsigned v) { return __hip_atomic_fetch_add(p, v, __ATOMIC_RELAXED, __HIP_MEMORY_SCOPE_AGENT); }
; __device__ __forceinline__ void xcd_barrier(const XcdBarrier& b) {
;     ...
;             __builtin_amdgcn_fence(__ATOMIC_ACQUIRE, "agent");
;             xb_add(&bar[XB_XGEN(b.x)], 1u);
;             asm volatile("s_waitcnt vmcnt(0)" ::: "memory");
.Llb_2:
	v_mov_b32_e32 v1, s25
	v_add_co_u32_e32 v2, vcc, 0x2000, v1
	v_mov_b32_e32 v1, s24
	s_nop 0
	v_addc_co_u32_e32 v3, vcc, 0, v1, vcc
	s_waitcnt vmcnt(0) lgkmcnt(0)
	buffer_inv sc1
	flat_atomic_add v[2:3], v217 offset:1024
	s_waitcnt vmcnt(0)

; __device__ __forceinline__ unsigned xb_ld(unsigned* p)              { return __hip_atomic_load(p, __ATOMIC_RELAXED, __HIP_MEMORY_SCOPE_AGENT); }
; __device__ __forceinline__ unsigned xb_add(unsigned* p, unsigned v) { return __hip_atomic_fetch_add(p, v, __ATOMIC_RELAXED, __HIP_MEMORY_SCOPE_AGENT); }
; #define XB_SPIN(cond, bar) do { unsigned _sp = 0; while (cond) { __builtin_amdgcn_s_sleep(1); \
;     if ((++_sp & 255u) == 0u) { if (xb_ld(&(bar)[XB_TMO])) break; if (_sp > XB_SPIN_CAP) { atomicAdd(&(bar)[XB_TMO], 1u); break; } } } } while (0)
; __device__ __forceinline__ void xcd_barrier(const XcdBarrier& b) {
;     ...
;         if (old + 1u == (gen + 1u) * nloc) {
;             __builtin_amdgcn_fence(__ATOMIC_RELEASE, "agent");
;             asm volatile("s_waitcnt vmcnt(0)" ::: "memory");
;             const unsigned og = xb_add(&bar[XB_TOP], 1u);
;             const unsigned tg = og / nx;
;             if (og + 1u == (tg + 1u) * nx) xb_add(&bar[XB_TOPGEN], 1u);
;             else XB_SPIN(xb_ld(&bar[XB_TOPGEN]) == tg, bar);
.LBB0_605:
	s_andn2_saveexec_b64 s[4:5], s[4:5]
	s_cbranch_execz .LBB0_621
	s_branch .Llb_0
	v_mov_b32_e32 v1, s2
	v_add_co_u32_e32 v4, vcc, 0x3000, v1
	v_mov_b32_e32 v1, s3
	buffer_wbl2 sc1
	s_waitcnt vmcnt(0)
	v_addc_co_u32_e32 v5, vcc, 0, v1, vcc
	flat_atomic_add v3, v[4:5], v217 offset:1024 sc0
	v_cvt_f32_u32_e32 v1, v2
	v_sub_u32_e32 v4, 0, v2
	s_mov_b64 s[8:9], -1
	v_rcp_iflag_f32_e32 v1, v1
	s_nop 0
	v_mul_f32_e32 v1, 0x4f7ffffe, v1
	v_cvt_u32_f32_e32 v1, v1
	v_mul_lo_u32 v4, v4, v1
	v_mul_hi_u32 v4, v1, v4
	v_add_u32_e32 v1, v1, v4
	s_waitcnt vmcnt(0) lgkmcnt(0)
	v_mul_hi_u32 v1, v3, v1
	v_mul_lo_u32 v4, v1, v2
	v_sub_u32_e32 v4, v3, v4
	v_cmp_ge_u32_e32 vcc, v4, v2
	v_add_u32_e32 v5, 1, v1
	s_nop 0
	v_cndmask_b32_e32 v1, v1, v5, vcc
	v_sub_u32_e32 v5, v4, v2
	v_cndmask_b32_e32 v4, v4, v5, vcc
	v_cmp_ge_u32_e32 vcc, v4, v2
	v_add_u32_e32 v4, 1, v1
	s_nop 0
	v_cndmask_b32_e32 v1, v1, v4, vcc
	v_add_u32_e32 v4, 1, v3
	v_mad_u64_u32 v[2:3], s[4:5], v2, v1, v[2:3]
	s_add_u32 s4, s2, 0x3500
	s_addc_u32 s5, s3, 0
	v_cmp_ne_u32_e32 vcc, v4, v2
	v_mov_b64_e32 v[2:3], s[4:5]
	s_and_saveexec_b64 s[6:7], vcc
	s_cbranch_execz .LBB0_618
	v_mov_b64_e32 v[2:3], s[4:5]
	flat_load_dword v2, v[2:3] sc1
	s_mov_b64 s[12:13], 0
	s_waitcnt vmcnt(0) lgkmcnt(0)
	v_cmp_eq_u32_e32 vcc, v2, v1
	s_and_saveexec_b64 s[10:11], vcc
	s_cbranch_execz .LBB0_617
	s_add_u32 s8, s2, 0x200
	s_addc_u32 s9, s3, 0
	s_mov_b32 s22, 1
	s_mov_b64 s[2:3], 0
	s_branch .LBB0_610
